# moba-tile-K-V-fragment-prefetch-8buf
# baseline (speedup 1.0000x reference)
.LBB0_74:
	v_add_u32_e32 v169, s9, v148
	v_add_u32_e32 v183, v169, v149
	v_add_u32_e32 v184, v169, v150
	v_add_u32_e32 v185, v169, v151
	v_add_u32_e32 v186, v169, v152
	ds_read_b128 v[188:191], v183
	ds_read_b128 v[192:195], v183 offset:8192
	ds_read_b128 v[198:201], v184
	ds_read_b128 v[202:205], v184 offset:8192
	ds_read_b128 v[206:209], v185
	ds_read_b128 v[210:213], v185 offset:8192
	ds_read_b128 v[214:217], v186
	ds_read_b128 v[218:221], v186 offset:8192
	s_add_i32 s10, s6, 0x80
	v_cmp_gt_i32_e32 vcc, s10, v167
	s_and_b64 s[10:11], s[36:37], vcc
	v_add_u32_e32 v187, v169, v153
	v_add_u32_e32 v222, v169, v154
	v_add_u32_e32 v223, v169, v155
	v_add_u32_e32 v169, v169, v156
	s_waitcnt lgkmcnt(7)
	v_mfma_f32_32x32x16_bf16 v[80:95], v[188:191], v[98:101], 0
	ds_read_b128 v[188:191], v187
	s_waitcnt lgkmcnt(7)
	v_mfma_f32_32x32x16_bf16 v[64:79], v[192:195], v[98:101], 0
	ds_read_b128 v[192:195], v187 offset:8192
	s_waitcnt lgkmcnt(7)
	v_mfma_f32_32x32x16_bf16 v[80:95], v[198:201], v[102:105], v[80:95]
	ds_read_b128 v[198:201], v222
	s_waitcnt lgkmcnt(7)
	v_mfma_f32_32x32x16_bf16 v[64:79], v[202:205], v[102:105], v[64:79]
	ds_read_b128 v[202:205], v222 offset:8192
	s_waitcnt lgkmcnt(7)
	v_mfma_f32_32x32x16_bf16 v[80:95], v[206:209], v[106:109], v[80:95]
	ds_read_b128 v[206:209], v223
	s_waitcnt lgkmcnt(7)
	v_mfma_f32_32x32x16_bf16 v[64:79], v[210:213], v[106:109], v[64:79]
	ds_read_b128 v[210:213], v223 offset:8192
	s_waitcnt lgkmcnt(7)
	v_mfma_f32_32x32x16_bf16 v[80:95], v[214:217], v[110:113], v[80:95]
	ds_read_b128 v[214:217], v169
	s_waitcnt lgkmcnt(7)
	v_mfma_f32_32x32x16_bf16 v[64:79], v[218:221], v[110:113], v[64:79]
	ds_read_b128 v[218:221], v169 offset:8192
	v_add_u32_e32 v183, s9, v159
	v_add3_u32 v183, v183, v160, v157
	v_add_u32_e32 v184, v183, v161
	v_add_u32_e32 v185, v183, v162
	v_add_u32_e32 v186, v183, v163
	v_add_u32_e32 v183, v183, v158
	s_waitcnt lgkmcnt(7)
	v_mfma_f32_32x32x16_bf16 v[80:95], v[188:191], v[114:117], v[80:95]
	ds_read_b64_tr_b16 v[188:189], v183 offset:16384
	ds_read_b64_tr_b16 v[190:191], v183 offset:18432
	s_waitcnt lgkmcnt(8)
	v_mfma_f32_32x32x16_bf16 v[64:79], v[192:195], v[114:117], v[64:79]
	ds_read_b64_tr_b16 v[192:193], v184 offset:16384
	ds_read_b64_tr_b16 v[194:195], v184 offset:18432
	s_waitcnt lgkmcnt(9)
	v_mfma_f32_32x32x16_bf16 v[80:95], v[198:201], v[118:121], v[80:95]
	ds_read_b64_tr_b16 v[198:199], v185 offset:16384
	ds_read_b64_tr_b16 v[200:201], v185 offset:18432
	s_waitcnt lgkmcnt(10)
	v_mfma_f32_32x32x16_bf16 v[64:79], v[202:205], v[118:121], v[64:79]
	ds_read_b64_tr_b16 v[202:203], v186 offset:16384
	ds_read_b64_tr_b16 v[204:205], v186 offset:18432
	s_waitcnt lgkmcnt(11)
	v_mfma_f32_32x32x16_bf16 v[80:95], v[206:209], v[122:125], v[80:95]
	ds_read_b64_tr_b16 v[206:207], v183 offset:20480
	ds_read_b64_tr_b16 v[208:209], v183 offset:22528
	s_waitcnt lgkmcnt(12)
	v_mfma_f32_32x32x16_bf16 v[64:79], v[210:213], v[122:125], v[64:79]
	ds_read_b64_tr_b16 v[210:211], v184 offset:20480
	ds_read_b64_tr_b16 v[212:213], v184 offset:22528
	s_waitcnt lgkmcnt(13)
	v_mfma_f32_32x32x16_bf16 v[80:95], v[214:217], v[126:129], v[80:95]
	ds_read_b64_tr_b16 v[214:215], v185 offset:20480
	ds_read_b64_tr_b16 v[216:217], v185 offset:22528
	s_waitcnt lgkmcnt(14)
	v_mfma_f32_32x32x16_bf16 v[64:79], v[218:221], v[126:129], v[64:79]
	ds_read_b64_tr_b16 v[218:219], v186 offset:20480
	ds_read_b64_tr_b16 v[220:221], v186 offset:22528
	s_and_saveexec_b64 s[40:41], s[10:11]
	s_cbranch_execz .LBB0_76
	v_sub_u32_e32 v169, v140, v146
	v_cmp_lt_i32_e32 vcc, -1, v169
	s_nop 4
	v_cndmask_b32_e32 v80, v235, v80, vcc
	v_cmp_lt_i32_e32 vcc, 0, v169
	s_nop 1
	v_cndmask_b32_e32 v81, v235, v81, vcc
	v_cmp_lt_i32_e32 vcc, 1, v169
	s_nop 1
	v_cndmask_b32_e32 v82, v235, v82, vcc
	v_cmp_lt_i32_e32 vcc, 2, v169
	s_nop 1
	v_cndmask_b32_e32 v83, v235, v83, vcc
	v_cmp_lt_i32_e32 vcc, 7, v169
	s_nop 1
	v_cndmask_b32_e32 v84, v235, v84, vcc
	v_cmp_lt_i32_e32 vcc, 8, v169
	s_nop 1
	v_cndmask_b32_e32 v85, v235, v85, vcc
	v_cmp_lt_i32_e32 vcc, 9, v169
	s_nop 1
	v_cndmask_b32_e32 v86, v235, v86, vcc
	v_cmp_lt_i32_e32 vcc, 10, v169
	s_nop 1
	v_cndmask_b32_e32 v87, v235, v87, vcc
	v_cmp_lt_i32_e32 vcc, 15, v169
	s_nop 1
	v_cndmask_b32_e32 v88, v235, v88, vcc
	v_cmp_lt_i32_e32 vcc, 16, v169
	s_nop 1
	v_cndmask_b32_e32 v89, v235, v89, vcc
	v_cmp_lt_i32_e32 vcc, 17, v169
	s_nop 1
	v_cndmask_b32_e32 v90, v235, v90, vcc
	v_cmp_lt_i32_e32 vcc, 18, v169
	s_nop 1
	v_cndmask_b32_e32 v91, v235, v91, vcc
	v_cmp_lt_i32_e32 vcc, 23, v169
	s_nop 1
	v_cndmask_b32_e32 v92, v235, v92, vcc
	v_cmp_lt_i32_e32 vcc, 24, v169
	s_nop 1
	v_cndmask_b32_e32 v93, v235, v93, vcc
	v_cmp_lt_i32_e32 vcc, 25, v169
	s_nop 1
	v_cndmask_b32_e32 v94, v235, v94, vcc
	v_cmp_lt_i32_e32 vcc, 26, v169
	s_nop 1
	v_cndmask_b32_e32 v95, v235, v95, vcc
	v_cmp_lt_i32_e32 vcc, 31, v169
	s_nop 1
	v_cndmask_b32_e32 v64, v235, v64, vcc
	v_cmp_lt_i32_e32 vcc, 32, v169
	s_nop 1
	v_cndmask_b32_e32 v65, v235, v65, vcc
	v_cmp_lt_i32_e32 vcc, 33, v169
	s_nop 1
	v_cndmask_b32_e32 v66, v235, v66, vcc
	v_cmp_lt_i32_e32 vcc, 34, v169
	s_nop 1
	v_cndmask_b32_e32 v67, v235, v67, vcc
	v_cmp_lt_i32_e32 vcc, 39, v169
	s_nop 1
	v_cndmask_b32_e32 v68, v235, v68, vcc
	v_cmp_lt_i32_e32 vcc, 40, v169
	s_nop 1
	v_cndmask_b32_e32 v69, v235, v69, vcc
	v_cmp_lt_i32_e32 vcc, 41, v169
	s_nop 1
	v_cndmask_b32_e32 v70, v235, v70, vcc
	v_cmp_lt_i32_e32 vcc, 42, v169
	s_nop 1
	v_cndmask_b32_e32 v71, v235, v71, vcc
	v_cmp_lt_i32_e32 vcc, 47, v169
	s_nop 1
	v_cndmask_b32_e32 v72, v235, v72, vcc
	v_cmp_lt_i32_e32 vcc, 48, v169
	s_nop 1
	v_cndmask_b32_e32 v73, v235, v73, vcc
	v_cmp_lt_i32_e32 vcc, 49, v169
	s_nop 1
	v_cndmask_b32_e32 v74, v235, v74, vcc
	v_cmp_lt_i32_e32 vcc, 50, v169
	s_nop 1
	v_cndmask_b32_e32 v75, v235, v75, vcc
	v_cmp_lt_i32_e32 vcc, 55, v169
	s_nop 1
	v_cndmask_b32_e32 v76, v235, v76, vcc
	v_cmp_lt_i32_e32 vcc, 56, v169
	s_nop 1
	v_cndmask_b32_e32 v77, v235, v77, vcc
	v_cmp_lt_i32_e32 vcc, 57, v169
	s_nop 1
	v_cndmask_b32_e32 v78, v235, v78, vcc
	v_cmp_lt_i32_e32 vcc, 58, v169
	s_nop 1
	v_cndmask_b32_e32 v79, v235, v79, vcc

.LBB0_78:
	v_cndmask_b32_e64 v142, v236, v169, s[40:41]
	v_cndmask_b32_e64 v142, v142, v171, s[36:37]
	v_sub_f32_e32 v80, v80, v142
	v_exp_f32_e32 v171, v80
	v_sub_f32_e32 v81, v81, v142
	v_sub_f32_e32 v69, v69, v142
	v_exp_f32_e32 v81, v81
	v_sub_f32_e32 v82, v82, v142
	v_exp_f32_e32 v173, v69
	v_sub_f32_e32 v69, v70, v142
	v_exp_f32_e32 v82, v82
	v_sub_f32_e32 v83, v83, v142
	v_exp_f32_e32 v174, v69
	v_sub_f32_e32 v69, v71, v142
	v_exp_f32_e32 v83, v83
	v_sub_f32_e32 v84, v84, v142
	v_exp_f32_e32 v71, v69
	v_sub_f32_e32 v69, v72, v142
	v_add_f32_e32 v80, 0, v171
	v_exp_f32_e32 v84, v84
	v_sub_f32_e32 v85, v85, v142
	v_exp_f32_e32 v175, v69
	v_sub_f32_e32 v69, v73, v142
	v_add_f32_e32 v80, v81, v80
	v_exp_f32_e32 v85, v85
	v_sub_f32_e32 v86, v86, v142
	v_sub_f32_e32 v87, v87, v142
	v_exp_f32_e32 v176, v69
	v_sub_f32_e32 v69, v74, v142
	v_add_f32_e32 v80, v82, v80
	v_exp_f32_e32 v86, v86
	v_exp_f32_e32 v87, v87
	v_exp_f32_e32 v177, v69
	v_sub_f32_e32 v69, v75, v142
	v_add_f32_e32 v80, v83, v80
	v_exp_f32_e32 v178, v69
	v_sub_f32_e32 v69, v76, v142
	v_add_f32_e32 v80, v84, v80
	v_exp_f32_e32 v179, v69
	v_sub_f32_e32 v69, v77, v142
	v_cvt_pk_bf16_f32 v76, v171, v81
	v_add_f32_e32 v80, v85, v80
	v_exp_f32_e32 v180, v69
	v_sub_f32_e32 v69, v78, v142
	v_add_f32_e32 v80, v86, v80
	v_exp_f32_e32 v181, v69
	v_sub_f32_e32 v69, v79, v142
	v_cvt_pk_bf16_f32 v79, v86, v87
	v_cvt_pk_bf16_f32 v77, v82, v83
	v_cvt_pk_bf16_f32 v78, v84, v85
	v_add_f32_e32 v80, v87, v80
	v_sub_f32_e32 v88, v88, v142
	v_sub_f32_e32 v89, v89, v142
	v_exp_f32_e32 v88, v88
	v_exp_f32_e32 v89, v89
	s_waitcnt lgkmcnt(14)
	v_mfma_f32_32x32x16_bf16 v[48:63], v[188:191], v[76:79], v[48:63]
	ds_read_b64_tr_b16 v[188:189], v183 offset:24576
	ds_read_b64_tr_b16 v[190:191], v183 offset:26624
	v_add_f32_e32 v80, v88, v80
	v_cvt_pk_bf16_f32 v72, v88, v89
	v_sub_f32_e32 v90, v90, v142
	v_exp_f32_e32 v90, v90
	s_waitcnt lgkmcnt(14)
	v_mfma_f32_32x32x16_bf16 v[32:47], v[192:195], v[76:79], v[32:47]
	ds_read_b64_tr_b16 v[192:193], v184 offset:24576
	ds_read_b64_tr_b16 v[194:195], v184 offset:26624
	v_sub_f32_e32 v91, v91, v142
	v_sub_f32_e32 v92, v92, v142
	v_sub_f32_e32 v93, v93, v142
	v_sub_f32_e32 v94, v94, v142
	v_sub_f32_e32 v95, v95, v142
	v_exp_f32_e32 v91, v91
	s_waitcnt lgkmcnt(14)
	v_mfma_f32_32x32x16_bf16 v[16:31], v[198:201], v[76:79], v[16:31]
	ds_read_b64_tr_b16 v[198:199], v185 offset:24576
	ds_read_b64_tr_b16 v[200:201], v185 offset:26624
	v_exp_f32_e32 v92, v92
	v_exp_f32_e32 v93, v93
	v_exp_f32_e32 v94, v94
	v_exp_f32_e32 v95, v95
	v_add_f32_e32 v80, v89, v80
	v_add_f32_e32 v80, v90, v80
	s_waitcnt lgkmcnt(14)
	v_mfma_f32_32x32x16_bf16 v[0:15], v[202:205], v[76:79], v[0:15]
	ds_read_b64_tr_b16 v[202:203], v186 offset:24576
	ds_read_b64_tr_b16 v[204:205], v186 offset:26624
	v_add_f32_e32 v80, v91, v80
	v_sub_f32_e32 v64, v64, v142
	v_cvt_pk_bf16_f32 v73, v90, v91
	v_cvt_pk_bf16_f32 v74, v92, v93
	v_cvt_pk_bf16_f32 v75, v94, v95
	v_add_f32_e32 v80, v92, v80
	v_exp_f32_e32 v64, v64
	v_sub_f32_e32 v65, v65, v142
	s_waitcnt lgkmcnt(14)
	v_mfma_f32_32x32x16_bf16 v[48:63], v[206:209], v[72:75], v[48:63]
	ds_read_b64_tr_b16 v[206:207], v183 offset:28672
	ds_read_b64_tr_b16 v[208:209], v183 offset:30720
	v_add_f32_e32 v80, v93, v80
	v_exp_f32_e32 v65, v65
	v_sub_f32_e32 v66, v66, v142
	v_add_f32_e32 v80, v94, v80
	v_exp_f32_e32 v66, v66
	v_sub_f32_e32 v67, v67, v142
	v_add_f32_e32 v80, v95, v80
	v_exp_f32_e32 v67, v67
	v_sub_f32_e32 v68, v68, v142
	v_add_f32_e32 v80, v64, v80
	v_exp_f32_e32 v172, v68
	v_add_f32_e32 v80, v65, v80
	s_waitcnt lgkmcnt(14)
	v_mfma_f32_32x32x16_bf16 v[32:47], v[210:213], v[72:75], v[32:47]
	ds_read_b64_tr_b16 v[210:211], v184 offset:28672
	ds_read_b64_tr_b16 v[212:213], v184 offset:30720
	v_add_f32_e32 v80, v66, v80
	v_add_f32_e32 v80, v67, v80
	v_add_f32_e32 v68, v172, v80
	v_add_f32_e32 v68, v173, v68
	v_add_f32_e32 v68, v174, v68
	v_add_f32_e32 v68, v71, v68
	s_waitcnt lgkmcnt(14)
	v_mfma_f32_32x32x16_bf16 v[16:31], v[214:217], v[72:75], v[16:31]
	ds_read_b64_tr_b16 v[214:215], v185 offset:28672
	ds_read_b64_tr_b16 v[216:217], v185 offset:30720
	v_add_f32_e32 v68, v175, v68
	v_add_f32_e32 v68, v176, v68
	v_add_f32_e32 v68, v177, v68
	v_add_f32_e32 v68, v178, v68
	v_exp_f32_e32 v182, v69
	v_add_f32_e32 v68, v179, v68
	s_waitcnt lgkmcnt(14)
	v_mfma_f32_32x32x16_bf16 v[0:15], v[218:221], v[72:75], v[0:15]
	ds_read_b64_tr_b16 v[218:219], v186 offset:28672
	ds_read_b64_tr_b16 v[220:221], v186 offset:30720
	v_add_f32_e32 v68, v180, v68
	v_add_f32_e32 v68, v181, v68
	v_add_f32_e32 v80, v182, v68
	v_cvt_pk_bf16_f32 v68, v64, v65
	v_cvt_pk_bf16_f32 v69, v66, v67
	v_cvt_pk_bf16_f32 v70, v172, v173
	v_cvt_pk_bf16_f32 v71, v174, v71
	v_cvt_pk_bf16_f32 v64, v175, v176
	v_cvt_pk_bf16_f32 v65, v177, v178
	s_waitcnt lgkmcnt(14)
	v_mfma_f32_32x32x16_bf16 v[48:63], v[188:191], v[68:71], v[48:63]
	v_cvt_pk_bf16_f32 v66, v179, v180
	v_cvt_pk_bf16_f32 v67, v181, v182
	v_fmac_f32_e32 v80, v168, v140
	v_cndmask_b32_e64 v142, v170, v169, s[36:37]
	v_mov_b32_e32 v168, v80
	s_waitcnt lgkmcnt(12)
	v_mfma_f32_32x32x16_bf16 v[32:47], v[192:195], v[68:71], v[32:47]
	s_waitcnt lgkmcnt(10)
	v_mfma_f32_32x32x16_bf16 v[16:31], v[198:201], v[68:71], v[16:31]
	s_waitcnt lgkmcnt(8)
	v_mfma_f32_32x32x16_bf16 v[0:15], v[202:205], v[68:71], v[0:15]
	s_waitcnt lgkmcnt(6)
	v_mfma_f32_32x32x16_bf16 v[48:63], v[206:209], v[64:67], v[48:63]
	s_waitcnt lgkmcnt(4)
	v_mfma_f32_32x32x16_bf16 v[32:47], v[210:213], v[64:67], v[32:47]
	s_waitcnt lgkmcnt(2)
	v_mfma_f32_32x32x16_bf16 v[16:31], v[214:217], v[64:67], v[16:31]
	s_waitcnt lgkmcnt(0)
	v_mfma_f32_32x32x16_bf16 v[0:15], v[218:221], v[64:67], v[0:15]

.LBB0_84:
	v_add_u32_e32 v140, s9, v148
	v_add_u32_e32 v183, v140, v149
	v_add_u32_e32 v184, v140, v150
	v_add_u32_e32 v185, v140, v151
	v_add_u32_e32 v186, v140, v152
	ds_read_b128 v[188:191], v183 offset:32768
	ds_read_b128 v[192:195], v183 offset:40960
	ds_read_b128 v[198:201], v184 offset:32768
	ds_read_b128 v[202:205], v184 offset:40960
	ds_read_b128 v[206:209], v185 offset:32768
	ds_read_b128 v[210:213], v185 offset:40960
	ds_read_b128 v[214:217], v186 offset:32768
	ds_read_b128 v[218:221], v186 offset:40960
	s_add_i32 s10, s6, 0xc0
	v_cmp_gt_i32_e32 vcc, s10, v167
	s_and_b64 s[10:11], s[36:37], vcc
	v_add_u32_e32 v187, v140, v153
	v_add_u32_e32 v222, v140, v154
	v_add_u32_e32 v223, v140, v155
	v_add_u32_e32 v140, v140, v156
	s_waitcnt lgkmcnt(7)
	v_mfma_f32_32x32x16_bf16 v[80:95], v[188:191], v[98:101], 0
	ds_read_b128 v[188:191], v187 offset:32768
	s_waitcnt lgkmcnt(7)
	v_mfma_f32_32x32x16_bf16 v[64:79], v[192:195], v[98:101], 0
	ds_read_b128 v[192:195], v187 offset:40960
	s_waitcnt lgkmcnt(7)
	v_mfma_f32_32x32x16_bf16 v[80:95], v[198:201], v[102:105], v[80:95]
	ds_read_b128 v[198:201], v222 offset:32768
	s_waitcnt lgkmcnt(7)
	v_mfma_f32_32x32x16_bf16 v[64:79], v[202:205], v[102:105], v[64:79]
	ds_read_b128 v[202:205], v222 offset:40960
	s_waitcnt lgkmcnt(7)
	v_mfma_f32_32x32x16_bf16 v[80:95], v[206:209], v[106:109], v[80:95]
	ds_read_b128 v[206:209], v223 offset:32768
	s_waitcnt lgkmcnt(7)
	v_mfma_f32_32x32x16_bf16 v[64:79], v[210:213], v[106:109], v[64:79]
	ds_read_b128 v[210:213], v223 offset:40960
	s_waitcnt lgkmcnt(7)
	v_mfma_f32_32x32x16_bf16 v[80:95], v[214:217], v[110:113], v[80:95]
	ds_read_b128 v[214:217], v140 offset:32768
	s_waitcnt lgkmcnt(7)
	v_mfma_f32_32x32x16_bf16 v[64:79], v[218:221], v[110:113], v[64:79]
	ds_read_b128 v[218:221], v140 offset:40960
	v_add_u32_e32 v183, s9, v159
	v_add3_u32 v183, v183, v160, v157
	v_add_u32_e32 v184, v183, v161
	v_add_u32_e32 v185, v183, v162
	v_add_u32_e32 v186, v183, v163
	v_add_u32_e32 v183, v183, v158
	s_waitcnt lgkmcnt(7)
	v_mfma_f32_32x32x16_bf16 v[80:95], v[188:191], v[114:117], v[80:95]
	ds_read_b64_tr_b16 v[188:189], v183 offset:49152
	ds_read_b64_tr_b16 v[190:191], v183 offset:51200
	s_waitcnt lgkmcnt(8)
	v_mfma_f32_32x32x16_bf16 v[64:79], v[192:195], v[114:117], v[64:79]
	ds_read_b64_tr_b16 v[192:193], v184 offset:49152
	ds_read_b64_tr_b16 v[194:195], v184 offset:51200
	s_waitcnt lgkmcnt(9)
	v_mfma_f32_32x32x16_bf16 v[80:95], v[198:201], v[118:121], v[80:95]
	ds_read_b64_tr_b16 v[198:199], v185 offset:49152
	ds_read_b64_tr_b16 v[200:201], v185 offset:51200
	s_waitcnt lgkmcnt(10)
	v_mfma_f32_32x32x16_bf16 v[64:79], v[202:205], v[118:121], v[64:79]
	ds_read_b64_tr_b16 v[202:203], v186 offset:49152
	ds_read_b64_tr_b16 v[204:205], v186 offset:51200
	s_waitcnt lgkmcnt(11)
	v_mfma_f32_32x32x16_bf16 v[80:95], v[206:209], v[122:125], v[80:95]
	ds_read_b64_tr_b16 v[206:207], v183 offset:53248
	ds_read_b64_tr_b16 v[208:209], v183 offset:55296
	s_waitcnt lgkmcnt(12)
	v_mfma_f32_32x32x16_bf16 v[64:79], v[210:213], v[122:125], v[64:79]
	ds_read_b64_tr_b16 v[210:211], v184 offset:53248
	ds_read_b64_tr_b16 v[212:213], v184 offset:55296
	s_waitcnt lgkmcnt(13)
	v_mfma_f32_32x32x16_bf16 v[80:95], v[214:217], v[126:129], v[80:95]
	ds_read_b64_tr_b16 v[214:215], v185 offset:53248
	ds_read_b64_tr_b16 v[216:217], v185 offset:55296
	s_waitcnt lgkmcnt(14)
	v_mfma_f32_32x32x16_bf16 v[64:79], v[218:221], v[126:129], v[64:79]
	ds_read_b64_tr_b16 v[218:219], v186 offset:53248
	ds_read_b64_tr_b16 v[220:221], v186 offset:55296
	s_and_saveexec_b64 s[38:39], s[10:11]
	s_cbranch_execz .LBB0_86
	v_sub_u32_e32 v140, v133, v146
	v_cmp_lt_i32_e32 vcc, -1, v140
	s_nop 4
	v_cndmask_b32_e32 v80, v235, v80, vcc
	v_cmp_lt_i32_e32 vcc, 0, v140
	s_nop 1
	v_cndmask_b32_e32 v81, v235, v81, vcc
	v_cmp_lt_i32_e32 vcc, 1, v140
	s_nop 1
	v_cndmask_b32_e32 v82, v235, v82, vcc
	v_cmp_lt_i32_e32 vcc, 2, v140
	s_nop 1
	v_cndmask_b32_e32 v83, v235, v83, vcc
	v_cmp_lt_i32_e32 vcc, 7, v140
	s_nop 1
	v_cndmask_b32_e32 v84, v235, v84, vcc
	v_cmp_lt_i32_e32 vcc, 8, v140
	s_nop 1
	v_cndmask_b32_e32 v85, v235, v85, vcc
	v_cmp_lt_i32_e32 vcc, 9, v140
	s_nop 1
	v_cndmask_b32_e32 v86, v235, v86, vcc
	v_cmp_lt_i32_e32 vcc, 10, v140
	s_nop 1
	v_cndmask_b32_e32 v87, v235, v87, vcc
	v_cmp_lt_i32_e32 vcc, 15, v140
	s_nop 1
	v_cndmask_b32_e32 v88, v235, v88, vcc
	v_cmp_lt_i32_e32 vcc, 16, v140
	s_nop 1
	v_cndmask_b32_e32 v89, v235, v89, vcc
	v_cmp_lt_i32_e32 vcc, 17, v140
	s_nop 1
	v_cndmask_b32_e32 v90, v235, v90, vcc
	v_cmp_lt_i32_e32 vcc, 18, v140
	s_nop 1
	v_cndmask_b32_e32 v91, v235, v91, vcc
	v_cmp_lt_i32_e32 vcc, 23, v140
	s_nop 1
	v_cndmask_b32_e32 v92, v235, v92, vcc
	v_cmp_lt_i32_e32 vcc, 24, v140
	s_nop 1
	v_cndmask_b32_e32 v93, v235, v93, vcc
	v_cmp_lt_i32_e32 vcc, 25, v140
	s_nop 1
	v_cndmask_b32_e32 v94, v235, v94, vcc
	v_cmp_lt_i32_e32 vcc, 26, v140
	s_nop 1
	v_cndmask_b32_e32 v95, v235, v95, vcc
	v_cmp_lt_i32_e32 vcc, 31, v140
	s_nop 1
	v_cndmask_b32_e32 v64, v235, v64, vcc
	v_cmp_lt_i32_e32 vcc, 32, v140
	s_nop 1
	v_cndmask_b32_e32 v65, v235, v65, vcc
	v_cmp_lt_i32_e32 vcc, 33, v140
	s_nop 1
	v_cndmask_b32_e32 v66, v235, v66, vcc
	v_cmp_lt_i32_e32 vcc, 34, v140
	s_nop 1
	v_cndmask_b32_e32 v67, v235, v67, vcc
	v_cmp_lt_i32_e32 vcc, 39, v140
	s_nop 1
	v_cndmask_b32_e32 v68, v235, v68, vcc
	v_cmp_lt_i32_e32 vcc, 40, v140
	s_nop 1
	v_cndmask_b32_e32 v69, v235, v69, vcc
	v_cmp_lt_i32_e32 vcc, 41, v140
	s_nop 1
	v_cndmask_b32_e32 v70, v235, v70, vcc
	v_cmp_lt_i32_e32 vcc, 42, v140
	s_nop 1
	v_cndmask_b32_e32 v71, v235, v71, vcc
	v_cmp_lt_i32_e32 vcc, 47, v140
	s_nop 1
	v_cndmask_b32_e32 v72, v235, v72, vcc
	v_cmp_lt_i32_e32 vcc, 48, v140
	s_nop 1
	v_cndmask_b32_e32 v73, v235, v73, vcc
	v_cmp_lt_i32_e32 vcc, 49, v140
	s_nop 1
	v_cndmask_b32_e32 v74, v235, v74, vcc
	v_cmp_lt_i32_e32 vcc, 50, v140
	s_nop 1
	v_cndmask_b32_e32 v75, v235, v75, vcc
	v_cmp_lt_i32_e32 vcc, 55, v140
	s_nop 1
	v_cndmask_b32_e32 v76, v235, v76, vcc
	v_cmp_lt_i32_e32 vcc, 56, v140
	s_nop 1
	v_cndmask_b32_e32 v77, v235, v77, vcc
	v_cmp_lt_i32_e32 vcc, 57, v140
	s_nop 1
	v_cndmask_b32_e32 v78, v235, v78, vcc
	v_cmp_lt_i32_e32 vcc, 58, v140
	s_nop 1
	v_cndmask_b32_e32 v79, v235, v79, vcc

.LBB0_88:
	v_cndmask_b32_e64 v142, v236, v169, s[38:39]
	v_cndmask_b32_e64 v142, v142, v170, s[36:37]
	v_sub_f32_e32 v80, v80, v142
	v_exp_f32_e32 v170, v80
	v_sub_f32_e32 v81, v81, v142
	v_sub_f32_e32 v69, v69, v142
	v_exp_f32_e32 v81, v81
	v_sub_f32_e32 v82, v82, v142
	v_exp_f32_e32 v172, v69
	v_sub_f32_e32 v69, v70, v142
	v_exp_f32_e32 v82, v82
	v_sub_f32_e32 v83, v83, v142
	v_exp_f32_e32 v173, v69
	v_sub_f32_e32 v69, v71, v142
	v_exp_f32_e32 v83, v83
	v_sub_f32_e32 v84, v84, v142
	v_exp_f32_e32 v71, v69
	v_sub_f32_e32 v69, v72, v142
	v_add_f32_e32 v80, 0, v170
	v_exp_f32_e32 v84, v84
	v_sub_f32_e32 v85, v85, v142
	v_exp_f32_e32 v174, v69
	v_sub_f32_e32 v69, v73, v142
	v_add_f32_e32 v80, v81, v80
	v_exp_f32_e32 v85, v85
	v_sub_f32_e32 v86, v86, v142
	v_sub_f32_e32 v87, v87, v142
	v_exp_f32_e32 v175, v69
	v_sub_f32_e32 v69, v74, v142
	v_add_f32_e32 v80, v82, v80
	v_exp_f32_e32 v86, v86
	v_exp_f32_e32 v87, v87
	v_exp_f32_e32 v176, v69
	v_sub_f32_e32 v69, v75, v142
	v_add_f32_e32 v80, v83, v80
	v_exp_f32_e32 v177, v69
	v_sub_f32_e32 v69, v76, v142
	v_add_f32_e32 v80, v84, v80
	v_exp_f32_e32 v178, v69
	v_sub_f32_e32 v69, v77, v142
	v_cvt_pk_bf16_f32 v76, v170, v81
	v_add_f32_e32 v80, v85, v80
	v_exp_f32_e32 v179, v69
	v_sub_f32_e32 v69, v78, v142
	v_add_f32_e32 v80, v86, v80
	v_exp_f32_e32 v180, v69
	v_sub_f32_e32 v69, v79, v142
	v_cvt_pk_bf16_f32 v79, v86, v87
	v_cvt_pk_bf16_f32 v77, v82, v83
	v_cvt_pk_bf16_f32 v78, v84, v85
	v_add_f32_e32 v80, v87, v80
	v_sub_f32_e32 v88, v88, v142
	v_sub_f32_e32 v89, v89, v142
	v_exp_f32_e32 v88, v88
	v_exp_f32_e32 v89, v89
	s_waitcnt lgkmcnt(14)
	v_mfma_f32_32x32x16_bf16 v[48:63], v[188:191], v[76:79], v[48:63]
	ds_read_b64_tr_b16 v[188:189], v183 offset:57344
	ds_read_b64_tr_b16 v[190:191], v183 offset:59392
	v_add_f32_e32 v80, v88, v80
	v_cvt_pk_bf16_f32 v72, v88, v89
	v_sub_f32_e32 v90, v90, v142
	v_exp_f32_e32 v90, v90
	s_waitcnt lgkmcnt(14)
	v_mfma_f32_32x32x16_bf16 v[32:47], v[192:195], v[76:79], v[32:47]
	ds_read_b64_tr_b16 v[192:193], v184 offset:57344
	ds_read_b64_tr_b16 v[194:195], v184 offset:59392
	v_sub_f32_e32 v91, v91, v142
	v_sub_f32_e32 v92, v92, v142
	v_sub_f32_e32 v93, v93, v142
	v_sub_f32_e32 v94, v94, v142
	v_sub_f32_e32 v95, v95, v142
	v_exp_f32_e32 v91, v91
	s_waitcnt lgkmcnt(14)
	v_mfma_f32_32x32x16_bf16 v[16:31], v[198:201], v[76:79], v[16:31]
	ds_read_b64_tr_b16 v[198:199], v185 offset:57344
	ds_read_b64_tr_b16 v[200:201], v185 offset:59392
	v_exp_f32_e32 v92, v92
	v_exp_f32_e32 v93, v93
	v_exp_f32_e32 v94, v94
	v_exp_f32_e32 v95, v95
	v_add_f32_e32 v80, v89, v80
	v_add_f32_e32 v80, v90, v80
	s_waitcnt lgkmcnt(14)
	v_mfma_f32_32x32x16_bf16 v[0:15], v[202:205], v[76:79], v[0:15]
	ds_read_b64_tr_b16 v[202:203], v186 offset:57344
	ds_read_b64_tr_b16 v[204:205], v186 offset:59392
	v_add_f32_e32 v80, v91, v80
	v_sub_f32_e32 v64, v64, v142
	v_cvt_pk_bf16_f32 v73, v90, v91
	v_cvt_pk_bf16_f32 v74, v92, v93
	v_cvt_pk_bf16_f32 v75, v94, v95
	v_add_f32_e32 v80, v92, v80
	v_exp_f32_e32 v64, v64
	v_sub_f32_e32 v65, v65, v142
	s_waitcnt lgkmcnt(14)
	v_mfma_f32_32x32x16_bf16 v[48:63], v[206:209], v[72:75], v[48:63]
	ds_read_b64_tr_b16 v[206:207], v183 offset:61440
	ds_read_b64_tr_b16 v[208:209], v183 offset:63488
	v_add_f32_e32 v80, v93, v80
	v_exp_f32_e32 v65, v65
	v_sub_f32_e32 v66, v66, v142
	v_add_f32_e32 v80, v94, v80
	v_exp_f32_e32 v66, v66
	v_sub_f32_e32 v67, v67, v142
	v_add_f32_e32 v80, v95, v80
	v_exp_f32_e32 v67, v67
	v_sub_f32_e32 v68, v68, v142
	v_add_f32_e32 v80, v64, v80
	v_exp_f32_e32 v171, v68
	v_add_f32_e32 v80, v65, v80
	s_waitcnt lgkmcnt(14)
	v_mfma_f32_32x32x16_bf16 v[32:47], v[210:213], v[72:75], v[32:47]
	ds_read_b64_tr_b16 v[210:211], v184 offset:61440
	ds_read_b64_tr_b16 v[212:213], v184 offset:63488
	v_add_f32_e32 v80, v66, v80
	v_add_f32_e32 v80, v67, v80
	v_add_f32_e32 v68, v171, v80
	v_add_f32_e32 v68, v172, v68
	v_add_f32_e32 v68, v173, v68
	v_add_f32_e32 v68, v71, v68
	s_waitcnt lgkmcnt(14)
	v_mfma_f32_32x32x16_bf16 v[16:31], v[214:217], v[72:75], v[16:31]
	ds_read_b64_tr_b16 v[214:215], v185 offset:61440
	ds_read_b64_tr_b16 v[216:217], v185 offset:63488
	v_add_f32_e32 v68, v174, v68
	v_add_f32_e32 v68, v175, v68
	v_add_f32_e32 v68, v176, v68
	v_add_f32_e32 v68, v177, v68
	v_exp_f32_e32 v181, v69
	v_add_f32_e32 v68, v178, v68
	s_waitcnt lgkmcnt(14)
	v_mfma_f32_32x32x16_bf16 v[0:15], v[218:221], v[72:75], v[0:15]
	ds_read_b64_tr_b16 v[218:219], v186 offset:61440
	ds_read_b64_tr_b16 v[220:221], v186 offset:63488
	v_add_f32_e32 v68, v179, v68
	v_add_f32_e32 v68, v180, v68
	v_add_f32_e32 v80, v181, v68
	v_cvt_pk_bf16_f32 v68, v64, v65
	v_cvt_pk_bf16_f32 v69, v66, v67
	v_cvt_pk_bf16_f32 v70, v171, v172
	v_cvt_pk_bf16_f32 v71, v173, v71
	v_cvt_pk_bf16_f32 v64, v174, v175
	v_cvt_pk_bf16_f32 v65, v176, v177
	s_waitcnt lgkmcnt(14)
	v_mfma_f32_32x32x16_bf16 v[48:63], v[188:191], v[68:71], v[48:63]
	v_cvt_pk_bf16_f32 v66, v178, v179
	v_cvt_pk_bf16_f32 v67, v180, v181
	v_fmac_f32_e32 v80, v168, v140
	v_cndmask_b32_e64 v142, v133, v169, s[36:37]
	v_mov_b32_e32 v168, v80
	s_waitcnt lgkmcnt(12)
	v_mfma_f32_32x32x16_bf16 v[32:47], v[192:195], v[68:71], v[32:47]
	s_waitcnt lgkmcnt(10)
	v_mfma_f32_32x32x16_bf16 v[16:31], v[198:201], v[68:71], v[16:31]
	s_waitcnt lgkmcnt(8)
	v_mfma_f32_32x32x16_bf16 v[0:15], v[202:205], v[68:71], v[0:15]
	s_waitcnt lgkmcnt(6)
	v_mfma_f32_32x32x16_bf16 v[48:63], v[206:209], v[64:67], v[48:63]
	s_waitcnt lgkmcnt(4)
	v_mfma_f32_32x32x16_bf16 v[32:47], v[210:213], v[64:67], v[32:47]
	s_waitcnt lgkmcnt(2)
	v_mfma_f32_32x32x16_bf16 v[16:31], v[214:217], v[64:67], v[16:31]
	s_waitcnt lgkmcnt(0)
	v_mfma_f32_32x32x16_bf16 v[0:15], v[218:221], v[64:67], v[0:15]
